# baseline (speedup 1.0000x reference)
.LBB0_124:
	global_load_dword v164, v[10:11], off offset:-64
	s_cmp_lt_u32 s1, 2
	s_cselect_b64 vcc, -1, 0
	v_cndmask_b32_e32 v12, v148, v147, vcc
	s_nop 0
	s_add_i32 s88, s0, 16
	s_add_i32 s89, s0, 17
	s_add_i32 s90, s0, 18
	s_add_i32 s91, s0, 19
	s_add_i32 s92, s0, 20
	s_add_i32 s93, s0, 21
	s_add_i32 s94, s0, 22
	s_add_i32 s95, s0, 23
	v_readlane_b32 s88, v12, s88
	v_readlane_b32 s89, v12, s89
	v_readlane_b32 s90, v12, s90
	v_readlane_b32 s91, v12, s91
	v_readlane_b32 s92, v12, s92
	v_readlane_b32 s93, v12, s93
	v_readlane_b32 s94, v12, s94
	v_readlane_b32 s95, v12, s95
	s_lshl_b32 s88, s88, 9
	s_lshl_b32 s89, s89, 9
	s_lshl_b32 s90, s90, 9
	s_lshl_b32 s91, s91, 9
	s_lshl_b32 s92, s92, 9
	s_lshl_b32 s93, s93, 9
	s_lshl_b32 s94, s94, 9
	s_lshl_b32 s95, s95, 9
	buffer_load_dwordx2 v[42:43], v142, s[24:27], s88 offen
	buffer_load_dwordx2 v[40:41], v142, s[24:27], s89 offen
	buffer_load_dwordx2 v[38:39], v142, s[24:27], s90 offen
	buffer_load_dwordx2 v[36:37], v142, s[24:27], s91 offen
	buffer_load_dwordx2 v[34:35], v142, s[24:27], s92 offen
	buffer_load_dwordx2 v[32:33], v142, s[24:27], s93 offen
	buffer_load_dwordx2 v[30:31], v142, s[24:27], s94 offen
	buffer_load_dwordx2 v[28:29], v142, s[24:27], s95 offen
	s_add_i32 s88, s0, 24
	s_add_i32 s89, s0, 25
	s_add_i32 s90, s0, 26
	s_add_i32 s91, s0, 27
	s_add_i32 s92, s0, 28
	s_add_i32 s93, s0, 29
	s_add_i32 s94, s0, 30
	s_add_i32 s95, s0, 31
	v_readlane_b32 s88, v12, s88
	v_readlane_b32 s89, v12, s89
	v_readlane_b32 s90, v12, s90
	v_readlane_b32 s91, v12, s91
	v_readlane_b32 s92, v12, s92
	v_readlane_b32 s93, v12, s93
	v_readlane_b32 s94, v12, s94
	v_readlane_b32 s95, v12, s95
	s_lshl_b32 s88, s88, 9
	s_lshl_b32 s89, s89, 9
	s_lshl_b32 s90, s90, 9
	s_lshl_b32 s91, s91, 9
	s_lshl_b32 s92, s92, 9
	s_lshl_b32 s93, s93, 9
	s_lshl_b32 s94, s94, 9
	s_lshl_b32 s95, s95, 9
	buffer_load_dwordx2 v[26:27], v142, s[24:27], s88 offen
	buffer_load_dwordx2 v[24:25], v142, s[24:27], s89 offen
	buffer_load_dwordx2 v[22:23], v142, s[24:27], s90 offen
	buffer_load_dwordx2 v[20:21], v142, s[24:27], s91 offen
	buffer_load_dwordx2 v[18:19], v142, s[24:27], s92 offen
	buffer_load_dwordx2 v[16:17], v142, s[24:27], s93 offen
	buffer_load_dwordx2 v[14:15], v142, s[24:27], s94 offen
	buffer_load_dwordx2 v[12:13], v142, s[24:27], s95 offen
	s_waitcnt vmcnt(21)
	v_cvt_scalef32_pk_f16_fp4 v53, v82, 1.0
	v_mov_b32_e32 v54, v1
	v_dot2c_f32_f16_e32 v54, v53, v44
	v_cvt_scalef32_pk_f16_fp4 v53, v82, 1.0 op_sel:[1,0,0]
	v_dot2c_f32_f16_e32 v54, v53, v45
	v_cvt_scalef32_pk_f16_fp4 v53, v82, 1.0 op_sel:[0,1,0]
	v_dot2c_f32_f16_e32 v54, v53, v46
	v_cvt_scalef32_pk_f16_fp4 v53, v82, 1.0 op_sel:[1,1,0]
	v_dot2c_f32_f16_e32 v54, v53, v47
	v_cvt_scalef32_pk_f16_fp4 v53, v83, 1.0
	v_dot2c_f32_f16_e32 v54, v53, v48
	v_cvt_scalef32_pk_f16_fp4 v53, v83, 1.0 op_sel:[1,0,0]
	v_dot2c_f32_f16_e32 v54, v53, v49
	v_cvt_scalef32_pk_f16_fp4 v53, v83, 1.0 op_sel:[0,1,0]
	v_dot2c_f32_f16_e32 v54, v53, v50
	v_cvt_scalef32_pk_f16_fp4 v53, v83, 1.0 op_sel:[1,1,0]
	v_dot2c_f32_f16_e32 v54, v53, v51
	v_cvt_scalef32_pk_f16_fp4 v53, v86, 1.0
	v_mov_b32_e32 v55, v1
	v_dot2c_f32_f16_e32 v55, v53, v44
	v_cvt_scalef32_pk_f16_fp4 v53, v86, 1.0 op_sel:[1,0,0]
	v_dot2c_f32_f16_e32 v55, v53, v45
	v_cvt_scalef32_pk_f16_fp4 v53, v86, 1.0 op_sel:[0,1,0]
	v_dot2c_f32_f16_e32 v55, v53, v46
	v_cvt_scalef32_pk_f16_fp4 v53, v86, 1.0 op_sel:[1,1,0]
	v_dot2c_f32_f16_e32 v55, v53, v47
	v_cvt_scalef32_pk_f16_fp4 v53, v87, 1.0
	v_dot2c_f32_f16_e32 v55, v53, v48
	v_cvt_scalef32_pk_f16_fp4 v53, v87, 1.0 op_sel:[1,0,0]
	v_dot2c_f32_f16_e32 v55, v53, v49
	v_cvt_scalef32_pk_f16_fp4 v53, v87, 1.0 op_sel:[0,1,0]
	v_dot2c_f32_f16_e32 v55, v53, v50
	v_cvt_scalef32_pk_f16_fp4 v53, v87, 1.0 op_sel:[1,1,0]
	v_dot2c_f32_f16_e32 v55, v53, v51
	v_cvt_scalef32_pk_f16_fp4 v53, v84, 1.0
	v_mov_b32_e32 v56, v1
	v_dot2c_f32_f16_e32 v56, v53, v44
	v_cvt_scalef32_pk_f16_fp4 v53, v84, 1.0 op_sel:[1,0,0]
	v_dot2c_f32_f16_e32 v56, v53, v45
	v_cvt_scalef32_pk_f16_fp4 v53, v84, 1.0 op_sel:[0,1,0]
	v_dot2c_f32_f16_e32 v56, v53, v46
	v_cvt_scalef32_pk_f16_fp4 v53, v84, 1.0 op_sel:[1,1,0]
	v_dot2c_f32_f16_e32 v56, v53, v47
	v_cvt_scalef32_pk_f16_fp4 v53, v85, 1.0
	v_dot2c_f32_f16_e32 v56, v53, v48
	v_cvt_scalef32_pk_f16_fp4 v53, v85, 1.0 op_sel:[1,0,0]
	v_dot2c_f32_f16_e32 v56, v53, v49
	v_cvt_scalef32_pk_f16_fp4 v53, v85, 1.0 op_sel:[0,1,0]
	v_dot2c_f32_f16_e32 v56, v53, v50
	v_cvt_scalef32_pk_f16_fp4 v53, v85, 1.0 op_sel:[1,1,0]
	v_dot2c_f32_f16_e32 v56, v53, v51
	v_cvt_scalef32_pk_f16_fp4 v53, v88, 1.0
	v_mov_b32_e32 v57, v1
	v_dot2c_f32_f16_e32 v57, v53, v44
	v_cvt_scalef32_pk_f16_fp4 v53, v88, 1.0 op_sel:[1,0,0]
	v_dot2c_f32_f16_e32 v57, v53, v45
	v_cvt_scalef32_pk_f16_fp4 v53, v88, 1.0 op_sel:[0,1,0]
	v_dot2c_f32_f16_e32 v57, v53, v46
	v_cvt_scalef32_pk_f16_fp4 v53, v88, 1.0 op_sel:[1,1,0]
	v_dot2c_f32_f16_e32 v57, v53, v47
	v_cvt_scalef32_pk_f16_fp4 v53, v89, 1.0
	v_dot2c_f32_f16_e32 v57, v53, v48
	v_cvt_scalef32_pk_f16_fp4 v53, v89, 1.0 op_sel:[1,0,0]
	v_dot2c_f32_f16_e32 v57, v53, v49
	v_cvt_scalef32_pk_f16_fp4 v53, v89, 1.0 op_sel:[0,1,0]
	v_dot2c_f32_f16_e32 v57, v53, v50
	v_cvt_scalef32_pk_f16_fp4 v53, v89, 1.0 op_sel:[1,1,0]
	v_dot2c_f32_f16_e32 v57, v53, v51
	v_cvt_scalef32_pk_f16_fp4 v53, v94, 1.0
	v_mov_b32_e32 v58, v1
	v_dot2c_f32_f16_e32 v58, v53, v44
	v_cvt_scalef32_pk_f16_fp4 v53, v94, 1.0 op_sel:[1,0,0]
	v_dot2c_f32_f16_e32 v58, v53, v45
	v_cvt_scalef32_pk_f16_fp4 v53, v94, 1.0 op_sel:[0,1,0]
	v_dot2c_f32_f16_e32 v58, v53, v46
	v_cvt_scalef32_pk_f16_fp4 v53, v94, 1.0 op_sel:[1,1,0]
	v_dot2c_f32_f16_e32 v58, v53, v47
	v_cvt_scalef32_pk_f16_fp4 v53, v95, 1.0
	v_dot2c_f32_f16_e32 v58, v53, v48
	v_cvt_scalef32_pk_f16_fp4 v53, v95, 1.0 op_sel:[1,0,0]
	v_dot2c_f32_f16_e32 v58, v53, v49
	v_cvt_scalef32_pk_f16_fp4 v53, v95, 1.0 op_sel:[0,1,0]
	v_dot2c_f32_f16_e32 v58, v53, v50
	v_cvt_scalef32_pk_f16_fp4 v53, v95, 1.0 op_sel:[1,1,0]
	v_dot2c_f32_f16_e32 v58, v53, v51
	s_waitcnt vmcnt(19)
	v_cvt_scalef32_pk_f16_fp4 v53, v92, 1.0
	v_mov_b32_e32 v59, v1
	v_dot2c_f32_f16_e32 v59, v53, v44
	v_cvt_scalef32_pk_f16_fp4 v53, v92, 1.0 op_sel:[1,0,0]
	v_dot2c_f32_f16_e32 v59, v53, v45
	v_cvt_scalef32_pk_f16_fp4 v53, v92, 1.0 op_sel:[0,1,0]
	v_dot2c_f32_f16_e32 v59, v53, v46
	v_cvt_scalef32_pk_f16_fp4 v53, v92, 1.0 op_sel:[1,1,0]
	v_dot2c_f32_f16_e32 v59, v53, v47
	v_cvt_scalef32_pk_f16_fp4 v53, v93, 1.0
	v_dot2c_f32_f16_e32 v59, v53, v48
	v_cvt_scalef32_pk_f16_fp4 v53, v93, 1.0 op_sel:[1,0,0]
	v_dot2c_f32_f16_e32 v59, v53, v49
	v_cvt_scalef32_pk_f16_fp4 v53, v93, 1.0 op_sel:[0,1,0]
	v_dot2c_f32_f16_e32 v59, v53, v50
	v_cvt_scalef32_pk_f16_fp4 v53, v93, 1.0 op_sel:[1,1,0]
	v_dot2c_f32_f16_e32 v59, v53, v51
	v_cvt_scalef32_pk_f16_fp4 v53, v90, 1.0
	v_mov_b32_e32 v60, v1
	v_dot2c_f32_f16_e32 v60, v53, v44
	v_cvt_scalef32_pk_f16_fp4 v53, v90, 1.0 op_sel:[1,0,0]
	v_dot2c_f32_f16_e32 v60, v53, v45
	v_cvt_scalef32_pk_f16_fp4 v53, v90, 1.0 op_sel:[0,1,0]
	v_dot2c_f32_f16_e32 v60, v53, v46
	v_cvt_scalef32_pk_f16_fp4 v53, v90, 1.0 op_sel:[1,1,0]
	v_dot2c_f32_f16_e32 v60, v53, v47
	v_cvt_scalef32_pk_f16_fp4 v53, v91, 1.0
	v_dot2c_f32_f16_e32 v60, v53, v48
	v_cvt_scalef32_pk_f16_fp4 v53, v91, 1.0 op_sel:[1,0,0]
	v_dot2c_f32_f16_e32 v60, v53, v49
	v_cvt_scalef32_pk_f16_fp4 v53, v91, 1.0 op_sel:[0,1,0]
	v_dot2c_f32_f16_e32 v60, v53, v50
	v_cvt_scalef32_pk_f16_fp4 v53, v91, 1.0 op_sel:[1,1,0]
	v_dot2c_f32_f16_e32 v60, v53, v51
	v_cvt_scalef32_pk_f16_fp4 v53, v96, 1.0
	v_mov_b32_e32 v61, v1
	v_dot2c_f32_f16_e32 v61, v53, v44
	v_cvt_scalef32_pk_f16_fp4 v53, v96, 1.0 op_sel:[1,0,0]
	v_dot2c_f32_f16_e32 v61, v53, v45
	v_cvt_scalef32_pk_f16_fp4 v53, v96, 1.0 op_sel:[0,1,0]
	v_dot2c_f32_f16_e32 v61, v53, v46
	v_cvt_scalef32_pk_f16_fp4 v53, v96, 1.0 op_sel:[1,1,0]
	v_dot2c_f32_f16_e32 v61, v53, v47
	v_cvt_scalef32_pk_f16_fp4 v53, v97, 1.0
	v_dot2c_f32_f16_e32 v61, v53, v48
	v_cvt_scalef32_pk_f16_fp4 v53, v97, 1.0 op_sel:[1,0,0]
	v_dot2c_f32_f16_e32 v61, v53, v49
	v_cvt_scalef32_pk_f16_fp4 v53, v97, 1.0 op_sel:[0,1,0]
	v_dot2c_f32_f16_e32 v61, v53, v50
	v_cvt_scalef32_pk_f16_fp4 v53, v97, 1.0 op_sel:[1,1,0]
	v_dot2c_f32_f16_e32 v61, v53, v51
	v_cvt_scalef32_pk_f16_fp4 v53, v102, 1.0
	v_mov_b32_e32 v63, v1
	v_dot2c_f32_f16_e32 v63, v53, v44
	v_cvt_scalef32_pk_f16_fp4 v53, v102, 1.0 op_sel:[1,0,0]
	v_dot2c_f32_f16_e32 v63, v53, v45
	v_cvt_scalef32_pk_f16_fp4 v53, v102, 1.0 op_sel:[0,1,0]
	v_dot2c_f32_f16_e32 v63, v53, v46
	v_cvt_scalef32_pk_f16_fp4 v53, v102, 1.0 op_sel:[1,1,0]
	v_dot2c_f32_f16_e32 v63, v53, v47
	v_cvt_scalef32_pk_f16_fp4 v53, v103, 1.0
	v_dot2c_f32_f16_e32 v63, v53, v48
	v_cvt_scalef32_pk_f16_fp4 v53, v103, 1.0 op_sel:[1,0,0]
	v_dot2c_f32_f16_e32 v63, v53, v49
	v_cvt_scalef32_pk_f16_fp4 v53, v103, 1.0 op_sel:[0,1,0]
	v_dot2c_f32_f16_e32 v63, v53, v50
	v_cvt_scalef32_pk_f16_fp4 v53, v103, 1.0 op_sel:[1,1,0]
	v_dot2c_f32_f16_e32 v63, v53, v51
	s_waitcnt vmcnt(17)
	v_cvt_scalef32_pk_f16_fp4 v53, v100, 1.0
	v_mov_b32_e32 v82, v1
	v_dot2c_f32_f16_e32 v82, v53, v44
	v_cvt_scalef32_pk_f16_fp4 v53, v100, 1.0 op_sel:[1,0,0]
	v_dot2c_f32_f16_e32 v82, v53, v45
	v_cvt_scalef32_pk_f16_fp4 v53, v100, 1.0 op_sel:[0,1,0]
	v_dot2c_f32_f16_e32 v82, v53, v46
	v_cvt_scalef32_pk_f16_fp4 v53, v100, 1.0 op_sel:[1,1,0]
	v_dot2c_f32_f16_e32 v82, v53, v47
	v_cvt_scalef32_pk_f16_fp4 v53, v101, 1.0
	v_dot2c_f32_f16_e32 v82, v53, v48
	v_cvt_scalef32_pk_f16_fp4 v53, v101, 1.0 op_sel:[1,0,0]
	v_dot2c_f32_f16_e32 v82, v53, v49
	v_cvt_scalef32_pk_f16_fp4 v53, v101, 1.0 op_sel:[0,1,0]
	v_dot2c_f32_f16_e32 v82, v53, v50
	v_cvt_scalef32_pk_f16_fp4 v53, v101, 1.0 op_sel:[1,1,0]
	v_dot2c_f32_f16_e32 v82, v53, v51
	v_cvt_scalef32_pk_f16_fp4 v53, v98, 1.0
	v_mov_b32_e32 v83, v1
	v_dot2c_f32_f16_e32 v83, v53, v44
	v_cvt_scalef32_pk_f16_fp4 v53, v98, 1.0 op_sel:[1,0,0]
	v_dot2c_f32_f16_e32 v83, v53, v45
	v_cvt_scalef32_pk_f16_fp4 v53, v98, 1.0 op_sel:[0,1,0]
	v_dot2c_f32_f16_e32 v83, v53, v46
	v_cvt_scalef32_pk_f16_fp4 v53, v98, 1.0 op_sel:[1,1,0]
	v_dot2c_f32_f16_e32 v83, v53, v47
	v_cvt_scalef32_pk_f16_fp4 v53, v99, 1.0
	v_dot2c_f32_f16_e32 v83, v53, v48
	v_cvt_scalef32_pk_f16_fp4 v53, v99, 1.0 op_sel:[1,0,0]
	v_dot2c_f32_f16_e32 v83, v53, v49
	v_cvt_scalef32_pk_f16_fp4 v53, v99, 1.0 op_sel:[0,1,0]
	v_dot2c_f32_f16_e32 v83, v53, v50
	v_cvt_scalef32_pk_f16_fp4 v53, v99, 1.0 op_sel:[1,1,0]
	v_dot2c_f32_f16_e32 v83, v53, v51
	v_cvt_scalef32_pk_f16_fp4 v53, v104, 1.0
	v_mov_b32_e32 v84, v1
	v_dot2c_f32_f16_e32 v84, v53, v44
	v_cvt_scalef32_pk_f16_fp4 v53, v104, 1.0 op_sel:[1,0,0]
	v_dot2c_f32_f16_e32 v84, v53, v45
	v_cvt_scalef32_pk_f16_fp4 v53, v104, 1.0 op_sel:[0,1,0]
	v_dot2c_f32_f16_e32 v84, v53, v46
	v_cvt_scalef32_pk_f16_fp4 v53, v104, 1.0 op_sel:[1,1,0]
	v_dot2c_f32_f16_e32 v84, v53, v47
	v_cvt_scalef32_pk_f16_fp4 v53, v105, 1.0
	v_dot2c_f32_f16_e32 v84, v53, v48
	v_cvt_scalef32_pk_f16_fp4 v53, v105, 1.0 op_sel:[1,0,0]
	v_dot2c_f32_f16_e32 v84, v53, v49
	v_cvt_scalef32_pk_f16_fp4 v53, v105, 1.0 op_sel:[0,1,0]
	v_dot2c_f32_f16_e32 v84, v53, v50
	v_cvt_scalef32_pk_f16_fp4 v53, v105, 1.0 op_sel:[1,1,0]
	v_dot2c_f32_f16_e32 v84, v53, v51
	v_cvt_scalef32_pk_f16_fp4 v53, v108, 1.0
	v_mov_b32_e32 v85, v1
	v_dot2c_f32_f16_e32 v85, v53, v44
	v_cvt_scalef32_pk_f16_fp4 v53, v108, 1.0 op_sel:[1,0,0]
; DEVI float geluf_(float x) { return 0.5f * x * (1.f + erff(x * 0.70710678118654752f)); }
	v_dot2c_f32_f16_e32 v85, v53, v45
	v_cvt_scalef32_pk_f16_fp4 v53, v108, 1.0 op_sel:[0,1,0]
	v_dot2c_f32_f16_e32 v85, v53, v46
	v_cvt_scalef32_pk_f16_fp4 v53, v108, 1.0 op_sel:[1,1,0]
	v_dot2c_f32_f16_e32 v85, v53, v47
	v_cvt_scalef32_pk_f16_fp4 v53, v109, 1.0
	v_dot2c_f32_f16_e32 v85, v53, v48
	v_cvt_scalef32_pk_f16_fp4 v53, v109, 1.0 op_sel:[1,0,0]
	v_dot2c_f32_f16_e32 v85, v53, v49
	v_cvt_scalef32_pk_f16_fp4 v53, v109, 1.0 op_sel:[0,1,0]
	v_dot2c_f32_f16_e32 v85, v53, v50
	v_cvt_scalef32_pk_f16_fp4 v53, v109, 1.0 op_sel:[1,1,0]
	v_dot2c_f32_f16_e32 v85, v53, v51
	v_cvt_scalef32_pk_f16_fp4 v53, v106, 1.0
	v_mov_b32_e32 v86, v1
	v_dot2c_f32_f16_e32 v86, v53, v44
	v_cvt_scalef32_pk_f16_fp4 v53, v106, 1.0 op_sel:[1,0,0]
	v_dot2c_f32_f16_e32 v86, v53, v45
	v_cvt_scalef32_pk_f16_fp4 v53, v106, 1.0 op_sel:[0,1,0]
	v_dot2c_f32_f16_e32 v86, v53, v46
	v_cvt_scalef32_pk_f16_fp4 v53, v106, 1.0 op_sel:[1,1,0]
	v_dot2c_f32_f16_e32 v86, v53, v47
	v_cvt_scalef32_pk_f16_fp4 v53, v107, 1.0
	v_dot2c_f32_f16_e32 v86, v53, v48
	v_cvt_scalef32_pk_f16_fp4 v53, v107, 1.0 op_sel:[1,0,0]
	v_dot2c_f32_f16_e32 v86, v53, v49
	v_cvt_scalef32_pk_f16_fp4 v53, v107, 1.0 op_sel:[0,1,0]
	v_dot2c_f32_f16_e32 v86, v53, v50
	v_cvt_scalef32_pk_f16_fp4 v53, v107, 1.0 op_sel:[1,1,0]
	v_dot2c_f32_f16_e32 v86, v53, v51
	v_cvt_scalef32_pk_f16_fp4 v53, v110, 1.0
	v_mov_b32_e32 v87, v1
	v_dot2c_f32_f16_e32 v87, v53, v44
	v_cvt_scalef32_pk_f16_fp4 v53, v110, 1.0 op_sel:[1,0,0]
	v_dot2c_f32_f16_e32 v87, v53, v45
	v_cvt_scalef32_pk_f16_fp4 v53, v110, 1.0 op_sel:[0,1,0]
	v_dot2c_f32_f16_e32 v87, v53, v46
	v_cvt_scalef32_pk_f16_fp4 v53, v110, 1.0 op_sel:[1,1,0]
	v_dot2c_f32_f16_e32 v87, v53, v47
	v_cvt_scalef32_pk_f16_fp4 v53, v111, 1.0
	v_dot2c_f32_f16_e32 v87, v53, v48
	v_cvt_scalef32_pk_f16_fp4 v53, v111, 1.0 op_sel:[1,0,0]
	v_dot2c_f32_f16_e32 v87, v53, v49
	v_cvt_scalef32_pk_f16_fp4 v53, v111, 1.0 op_sel:[0,1,0]
	v_dot2c_f32_f16_e32 v87, v53, v50
	v_cvt_scalef32_pk_f16_fp4 v53, v111, 1.0 op_sel:[1,1,0]
	v_dot2c_f32_f16_e32 v87, v53, v51
	v_cvt_scalef32_pk_f16_fp4 v53, v112, 1.0
	v_mov_b32_e32 v88, v1
	v_dot2c_f32_f16_e32 v88, v53, v44
	v_cvt_scalef32_pk_f16_fp4 v53, v112, 1.0 op_sel:[1,0,0]
	v_dot2c_f32_f16_e32 v88, v53, v45
	v_cvt_scalef32_pk_f16_fp4 v53, v112, 1.0 op_sel:[0,1,0]
	v_dot2c_f32_f16_e32 v88, v53, v46
	v_cvt_scalef32_pk_f16_fp4 v53, v112, 1.0 op_sel:[1,1,0]
	v_dot2c_f32_f16_e32 v88, v53, v47
	v_cvt_scalef32_pk_f16_fp4 v53, v113, 1.0
	v_dot2c_f32_f16_e32 v88, v53, v48
	v_cvt_scalef32_pk_f16_fp4 v53, v113, 1.0 op_sel:[1,0,0]
	v_dot2c_f32_f16_e32 v88, v53, v49
	v_cvt_scalef32_pk_f16_fp4 v53, v113, 1.0 op_sel:[0,1,0]
	v_dot2c_f32_f16_e32 v88, v53, v50
	v_cvt_scalef32_pk_f16_fp4 v53, v113, 1.0 op_sel:[1,1,0]
	v_dot2c_f32_f16_e32 v88, v53, v51
	v_permlane32_swap_b32_e32 v54, v63
	v_permlane32_swap_b32_e32 v55, v82
	v_permlane32_swap_b32_e32 v56, v83
	v_permlane32_swap_b32_e32 v57, v84
	v_permlane32_swap_b32_e32 v58, v85
	v_permlane32_swap_b32_e32 v59, v86
	v_permlane32_swap_b32_e32 v60, v87
	v_add_f32_e32 v53, v54, v63
	v_add_f32_e32 v54, v55, v82
	v_add_f32_e32 v55, v56, v83
	v_add_f32_e32 v56, v57, v84
	v_add_f32_e32 v57, v58, v85
	v_add_f32_e32 v58, v59, v86
	v_add_f32_e32 v59, v60, v87
	v_permlane32_swap_b32_e32 v61, v88
	v_add_f32_e32 v60, v61, v88
	v_permlane16_swap_b32_e32 v53, v57
	v_permlane16_swap_b32_e32 v55, v59
	v_add_f32_e32 v53, v53, v57
	v_permlane16_swap_b32_e32 v54, v58
	v_add_f32_e32 v55, v55, v59
	v_permlane16_swap_b32_e32 v56, v60
	v_add_f32_e32 v54, v54, v58
	v_add_f32_e32 v56, v56, v60
	v_add_f32_dpp v53, v53, v53 row_ror:8 row_mask:0xf bank_mask:0xf bound_ctrl:1
	v_add_f32_dpp v55, v55, v55 row_ror:8 row_mask:0xf bank_mask:0xf bound_ctrl:1
	v_cndmask_b32_e64 v53, v55, v53, s[38:39]
	v_add_f32_dpp v54, v54, v54 row_ror:8 row_mask:0xf bank_mask:0xf bound_ctrl:1
	v_add_f32_dpp v55, v56, v56 row_ror:8 row_mask:0xf bank_mask:0xf bound_ctrl:1
	v_cndmask_b32_e64 v54, v55, v54, s[38:39]
	v_cndmask_b32_e64 v55, v53, v54, s[40:41]
	v_cndmask_b32_e64 v53, v54, v53, s[40:41]
	ds_bpermute_b32 v55, v144, v55
	s_waitcnt lgkmcnt(0)
	v_add_f32_e32 v53, v53, v55
	s_nop 1
	v_add_f32_dpp v53, v53, v53 quad_perm:[2,3,0,1] row_mask:0xf bank_mask:0xf bound_ctrl:1
	s_nop 1
	v_add_f32_dpp v53, v53, v53 quad_perm:[1,0,3,2] row_mask:0xf bank_mask:0xf bound_ctrl:1
	v_mul_f32_e32 v53, 0x3caaaaab, v53
	v_mul_f32_e32 v55, 0x3f3504f3, v53
	v_cmp_nlt_f32_e64 s[2:3], |v55|, 1.0
	s_and_saveexec_b64 s[22:23], s[2:3]
	s_xor_b64 s[2:3], exec, s[22:23]
	s_cbranch_execz .LBB0_130
	v_fma_f32 v56, |v55|, s29, v223
	v_fma_f32 v56, |v55|, v56, s20
	v_fma_f32 v56, |v55|, v56, s21
	v_fma_f32 v56, |v55|, v56, s28
	v_fma_f32 v56, |v55|, v56, s33
	v_fma_f32 v56, |v55|, v56, s30
	v_fma_f32 v56, |v55|, v56, |v55|
	v_mul_f32_e32 v57, 0xbfb8aa3b, v56
	v_fma_f32 v58, v56, s31, -v57
	v_rndne_f32_e32 v59, v57
	v_fmac_f32_e32 v58, 0xb2a5705f, v56
	v_sub_f32_e32 v57, v57, v59
	v_add_f32_e32 v57, v57, v58
	v_cvt_i32_f32_e32 v58, v59
	v_exp_f32_e32 v57, v57
	v_cmp_nlt_f32_e32 vcc, s96, v56
	v_ldexp_f32 v57, v57, v58
	s_nop 0
	v_cndmask_b32_e32 v57, 0, v57, vcc
	v_cmp_ngt_f32_e32 vcc, s97, v56
	s_nop 1
	v_cndmask_b32_e32 v56, v224, v57, vcc
	v_sub_f32_e32 v56, 1.0, v56
	s_andn2_saveexec_b64 s[2:3], s[2:3]
	s_cbranch_execnz .LBB0_131

; DEVI float geluf_(float x) { return 0.5f * x * (1.f + erff(x * 0.70710678118654752f)); }
.LBB0_127:
	v_bfi_b32 v55, s78, v56, v55
	v_mul_f32_e32 v53, 0.5, v53
	v_add_f32_e32 v55, 1.0, v55
	v_mul_f32_e32 v53, v53, v55
	s_waitcnt vmcnt(16)
	v_mul_f32_e32 v53, v164, v53
	v_mul_f32_e32 v53, 0x3e70f0f1, v53
	v_cvt_pk_f16_f32 v53, v53, v53
	ds_write_b32 v52, v53
